# v19 + attention block-gating prologue de-serialised: all 32 kpart loads in flight into eight register sets, counted waits, then the eight MFMAs
# speedup vs baseline: 1.0015x; 1.0015x over previous
; __device__ __forceinline__ u32x4 pack8(const f32x4 a, const f32x4 b) { u32x4 w; w.x = cvt_pk_bf16(a[0], a[1]); w.y = cvt_pk_bf16(a[2], a[3]); w.z = cvt_pk_bf16(b[0], b[1]); w.w = cvt_pk_bf16(b[2], b[3]); return w; }
; #define MFMA32(a, b, c) __builtin_amdgcn_mfma_f32_32x32x16_bf16((a), (b), (c), 0, 0, 0)
; __device__ __forceinline__ void attn_phase(LAS unsigned char* lds, const bf16_t* Q, const bf16_t* Kb, const bf16_t* VT, const bf16_t* Z, const float* kpart, bf16_t* Y, int G, int bid) {
;     ...
;         const int bh = pair >> 2, jp = pair & 3, b = bh >> 4, h = bh & 15;
;         for (int half = 0; half < 2; ++half) {
;             const int own = half == 0 ? 7 - jp : jp;
;             const int q0 = own * 256 + wid * 32;
;             const size_t qoff = (size_t)(b * SEQ + q0 + qr) * DM + h * 128;
;             bf16x8 Qf[8];
; #pragma unroll
;             for (int ks = 0; ks < 8; ++ks) Qf[ks] = *(const bf16x8*)(Q + qoff + ks * 16 + hh * 8);
;             unsigned selmask = (1u << own) - 1u;
;             if (own > 3) {
;                 f32x16 gacc;
; #pragma unroll
;                 for (int j = 0; j < 16; ++j) gacc[j] = 0.f;
; #pragma unroll
;                 for (int ks = 0; ks < 8; ++ks) {
;                     u32x4 w = (u32x4){0u, 0u, 0u, 0u};
;                     if (qr < 8) {
;                         const float* kp = kpart + ((size_t)((b * 8 + qr) * 2)) * DM + h * 128 + ks * 16 + hh * 8;
;                         const f32x4 a0 = *(const f32x4*)(kp), a1 = *(const f32x4*)(kp + 4), c0 = *(const f32x4*)(kp + DM), c1 = *(const f32x4*)(kp + DM + 4);
;                         w = pack8((a0 + c0) * (1.0f / 256.0f), (a1 + c1) * (1.0f / 256.0f));
;                     }
;                     bf16x8 af; __builtin_memcpy(&af, &w, 16);
;                     gacc = MFMA32(af, Qf[ks], gacc);
.LBB0_641:
	s_and_b64 s[0:1], s[70:71], exec
	s_cselect_b32 s79, s75, s74
	s_lshl_b32 s80, s79, 8
	s_add_i32 s78, s80, s69
	v_add_u32_e32 v0, s78, v179
	v_ashrrev_i32_e32 v1, 31, v0
	v_lshlrev_b64 v[212:213], 11, v[0:1]
	v_or_b32_e32 v212, s77, v212
	v_lshl_add_u64 v[0:1], v[212:213], 1, v[146:147]
	global_load_dwordx4 v[96:99], v[0:1], off
	global_load_dwordx4 v[100:103], v[0:1], off offset:32
	global_load_dwordx4 v[104:107], v[0:1], off offset:64
	global_load_dwordx4 v[108:111], v[0:1], off offset:96
	global_load_dwordx4 v[112:115], v[0:1], off offset:128
	global_load_dwordx4 v[116:119], v[0:1], off offset:160
	global_load_dwordx4 v[120:123], v[0:1], off offset:192
	global_load_dwordx4 v[124:127], v[0:1], off offset:224
	s_lshl_b32 s0, -1, s79
	s_not_b32 s0, s0
	s_cmp_lt_u32 s79, 4
	v_mov_b32_e32 v181, s0
	s_cbranch_scc1 .LBB0_659
	v_mov_b32_e32 v0, 0
	v_mov_b32_e32 v1, 0
	v_mov_b32_e32 v2, 0
	v_mov_b32_e32 v3, 0
	v_mov_b32_e32 v16, 0
	v_mov_b32_e32 v17, 0
	v_mov_b32_e32 v18, 0
	v_mov_b32_e32 v19, 0
	v_mov_b32_e32 v32, 0
	v_mov_b32_e32 v33, 0
	v_mov_b32_e32 v34, 0
	v_mov_b32_e32 v35, 0
	v_mov_b32_e32 v48, 0
	v_mov_b32_e32 v49, 0
	v_mov_b32_e32 v50, 0
	v_mov_b32_e32 v51, 0
	v_mov_b32_e32 v64, 0
	v_mov_b32_e32 v65, 0
	v_mov_b32_e32 v66, 0
	v_mov_b32_e32 v67, 0
	v_mov_b32_e32 v80, 0
	v_mov_b32_e32 v81, 0
	v_mov_b32_e32 v82, 0
	v_mov_b32_e32 v83, 0
	v_mov_b32_e32 v128, 0
	v_mov_b32_e32 v129, 0
	v_mov_b32_e32 v130, 0
	v_mov_b32_e32 v131, 0
	v_mov_b32_e32 v218, 0
	v_mov_b32_e32 v219, 0
	v_mov_b32_e32 v220, 0
	v_mov_b32_e32 v221, 0
	s_and_saveexec_b64 s[0:1], s[4:5]
	s_cbranch_execz .Lgate_skip
	global_load_dwordx4 v[0:3], v[196:197], off
	global_load_dwordx4 v[4:7], v[190:191], off
	global_load_dwordx4 v[8:11], v[190:191], off offset:16
	global_load_dwordx4 v[12:15], v[196:197], off offset:16
	global_load_dwordx4 v[16:19], v[198:199], off
	global_load_dwordx4 v[20:23], v[190:191], off offset:64
	global_load_dwordx4 v[24:27], v[190:191], off offset:80
	global_load_dwordx4 v[28:31], v[198:199], off offset:16
	global_load_dwordx4 v[32:35], v[200:201], off
	global_load_dwordx4 v[36:39], v[190:191], off offset:128
	global_load_dwordx4 v[40:43], v[190:191], off offset:144
	global_load_dwordx4 v[44:47], v[200:201], off offset:16
	global_load_dwordx4 v[48:51], v[202:203], off
	global_load_dwordx4 v[52:55], v[190:191], off offset:192
	global_load_dwordx4 v[56:59], v[190:191], off offset:208
	global_load_dwordx4 v[60:63], v[202:203], off offset:16
	global_load_dwordx4 v[64:67], v[204:205], off
	global_load_dwordx4 v[68:71], v[190:191], off offset:256
	global_load_dwordx4 v[72:75], v[190:191], off offset:272
	global_load_dwordx4 v[76:79], v[204:205], off offset:16
	global_load_dwordx4 v[80:83], v[206:207], off
	global_load_dwordx4 v[84:87], v[190:191], off offset:320
	global_load_dwordx4 v[88:91], v[190:191], off offset:336
	global_load_dwordx4 v[92:95], v[206:207], off offset:16
	global_load_dwordx4 v[128:131], v[208:209], off
	global_load_dwordx4 v[132:135], v[190:191], off offset:384
	global_load_dwordx4 v[136:139], v[190:191], off offset:400
	global_load_dwordx4 v[140:143], v[208:209], off offset:16
	global_load_dwordx4 v[218:221], v[210:211], off
	global_load_dwordx4 v[222:225], v[190:191], off offset:448
	global_load_dwordx4 v[226:229], v[190:191], off offset:464
	global_load_dwordx4 v[230:233], v[210:211], off offset:16
	s_waitcnt vmcnt(28)
	v_pk_add_f32 v[2:3], v[6:7], v[2:3]
	v_pk_add_f32 v[0:1], v[4:5], v[0:1]
	v_pk_add_f32 v[4:5], v[10:11], v[14:15]
	v_pk_add_f32 v[6:7], v[8:9], v[12:13]
	v_pk_mul_f32 v[2:3], v[2:3], s[68:69] op_sel_hi:[1,0]
	v_pk_mul_f32 v[0:1], v[0:1], s[68:69] op_sel_hi:[1,0]
	v_pk_mul_f32 v[4:5], v[4:5], s[68:69] op_sel_hi:[1,0]
	v_pk_mul_f32 v[6:7], v[6:7], s[68:69] op_sel_hi:[1,0]
	v_cvt_pk_bf16_f32 v0, v0, v1
	v_cvt_pk_bf16_f32 v1, v2, v3
	s_nop 0
	v_cvt_pk_bf16_f32 v2, v6, v7
	v_cvt_pk_bf16_f32 v3, v4, v5
	s_waitcnt vmcnt(24)
	v_pk_add_f32 v[18:19], v[22:23], v[18:19]
	v_pk_add_f32 v[16:17], v[20:21], v[16:17]
	v_pk_add_f32 v[20:21], v[26:27], v[30:31]
	v_pk_add_f32 v[22:23], v[24:25], v[28:29]
	v_pk_mul_f32 v[18:19], v[18:19], s[68:69] op_sel_hi:[1,0]
	v_pk_mul_f32 v[16:17], v[16:17], s[68:69] op_sel_hi:[1,0]
	v_pk_mul_f32 v[20:21], v[20:21], s[68:69] op_sel_hi:[1,0]
	v_pk_mul_f32 v[22:23], v[22:23], s[68:69] op_sel_hi:[1,0]
	v_cvt_pk_bf16_f32 v16, v16, v17
	v_cvt_pk_bf16_f32 v17, v18, v19
	s_nop 0
	v_cvt_pk_bf16_f32 v18, v22, v23
	v_cvt_pk_bf16_f32 v19, v20, v21
	s_waitcnt vmcnt(20)
	v_pk_add_f32 v[34:35], v[38:39], v[34:35]
	v_pk_add_f32 v[32:33], v[36:37], v[32:33]
	v_pk_add_f32 v[36:37], v[42:43], v[46:47]
	v_pk_add_f32 v[38:39], v[40:41], v[44:45]
	v_pk_mul_f32 v[34:35], v[34:35], s[68:69] op_sel_hi:[1,0]
	v_pk_mul_f32 v[32:33], v[32:33], s[68:69] op_sel_hi:[1,0]
	v_pk_mul_f32 v[36:37], v[36:37], s[68:69] op_sel_hi:[1,0]
	v_pk_mul_f32 v[38:39], v[38:39], s[68:69] op_sel_hi:[1,0]
	v_cvt_pk_bf16_f32 v32, v32, v33
	v_cvt_pk_bf16_f32 v33, v34, v35
	s_nop 0
	v_cvt_pk_bf16_f32 v34, v38, v39
	v_cvt_pk_bf16_f32 v35, v36, v37
	s_waitcnt vmcnt(16)
	v_pk_add_f32 v[50:51], v[54:55], v[50:51]
	v_pk_add_f32 v[48:49], v[52:53], v[48:49]
	v_pk_add_f32 v[52:53], v[58:59], v[62:63]
	v_pk_add_f32 v[54:55], v[56:57], v[60:61]
	v_pk_mul_f32 v[50:51], v[50:51], s[68:69] op_sel_hi:[1,0]
	v_pk_mul_f32 v[48:49], v[48:49], s[68:69] op_sel_hi:[1,0]
	v_pk_mul_f32 v[52:53], v[52:53], s[68:69] op_sel_hi:[1,0]
	v_pk_mul_f32 v[54:55], v[54:55], s[68:69] op_sel_hi:[1,0]
	v_cvt_pk_bf16_f32 v48, v48, v49
	v_cvt_pk_bf16_f32 v49, v50, v51
	s_nop 0
	v_cvt_pk_bf16_f32 v50, v54, v55
	v_cvt_pk_bf16_f32 v51, v52, v53
	s_waitcnt vmcnt(12)
; __device__ __forceinline__ u32x4 pack8(const f32x4 a, const f32x4 b) { u32x4 w; w.x = cvt_pk_bf16(a[0], a[1]); w.y = cvt_pk_bf16(a[2], a[3]); w.z = cvt_pk_bf16(b[0], b[1]); w.w = cvt_pk_bf16(b[2], b[3]); return w; }
; #define MFMA32(a, b, c) __builtin_amdgcn_mfma_f32_32x32x16_bf16((a), (b), (c), 0, 0, 0)
; __device__ __forceinline__ void attn_phase(LAS unsigned char* lds, const bf16_t* Q, const bf16_t* Kb, const bf16_t* VT, const bf16_t* Z, const float* kpart, bf16_t* Y, int G, int bid) {
;     ...
;                 for (int ks = 0; ks < 8; ++ks) {
;                     u32x4 w = (u32x4){0u, 0u, 0u, 0u};
;                     if (qr < 8) {
;                         const float* kp = kpart + ((size_t)((b * 8 + qr) * 2)) * DM + h * 128 + ks * 16 + hh * 8;
;                         const f32x4 a0 = *(const f32x4*)(kp), a1 = *(const f32x4*)(kp + 4), c0 = *(const f32x4*)(kp + DM), c1 = *(const f32x4*)(kp + DM + 4);
;                         w = pack8((a0 + c0) * (1.0f / 256.0f), (a1 + c1) * (1.0f / 256.0f));
;                     }
;                     bf16x8 af; __builtin_memcpy(&af, &w, 16);
;                     gacc = MFMA32(af, Qf[ks], gacc);
;                 }
	v_pk_add_f32 v[66:67], v[70:71], v[66:67]
	v_pk_add_f32 v[64:65], v[68:69], v[64:65]
	v_pk_add_f32 v[68:69], v[74:75], v[78:79]
	v_pk_add_f32 v[70:71], v[72:73], v[76:77]
	v_pk_mul_f32 v[66:67], v[66:67], s[68:69] op_sel_hi:[1,0]
	v_pk_mul_f32 v[64:65], v[64:65], s[68:69] op_sel_hi:[1,0]
	v_pk_mul_f32 v[68:69], v[68:69], s[68:69] op_sel_hi:[1,0]
	v_pk_mul_f32 v[70:71], v[70:71], s[68:69] op_sel_hi:[1,0]
	v_cvt_pk_bf16_f32 v64, v64, v65
	v_cvt_pk_bf16_f32 v65, v66, v67
	s_nop 0
	v_cvt_pk_bf16_f32 v66, v70, v71
	v_cvt_pk_bf16_f32 v67, v68, v69
	s_waitcnt vmcnt(8)
	v_pk_add_f32 v[82:83], v[86:87], v[82:83]
	v_pk_add_f32 v[80:81], v[84:85], v[80:81]
	v_pk_add_f32 v[84:85], v[90:91], v[94:95]
	v_pk_add_f32 v[86:87], v[88:89], v[92:93]
	v_pk_mul_f32 v[82:83], v[82:83], s[68:69] op_sel_hi:[1,0]
	v_pk_mul_f32 v[80:81], v[80:81], s[68:69] op_sel_hi:[1,0]
	v_pk_mul_f32 v[84:85], v[84:85], s[68:69] op_sel_hi:[1,0]
	v_pk_mul_f32 v[86:87], v[86:87], s[68:69] op_sel_hi:[1,0]
	v_cvt_pk_bf16_f32 v80, v80, v81
	v_cvt_pk_bf16_f32 v81, v82, v83
	s_nop 0
	v_cvt_pk_bf16_f32 v82, v86, v87
	v_cvt_pk_bf16_f32 v83, v84, v85
	s_waitcnt vmcnt(4)
	v_pk_add_f32 v[130:131], v[134:135], v[130:131]
	v_pk_add_f32 v[128:129], v[132:133], v[128:129]
	v_pk_add_f32 v[132:133], v[138:139], v[142:143]
	v_pk_add_f32 v[134:135], v[136:137], v[140:141]
	v_pk_mul_f32 v[130:131], v[130:131], s[68:69] op_sel_hi:[1,0]
	v_pk_mul_f32 v[128:129], v[128:129], s[68:69] op_sel_hi:[1,0]
	v_pk_mul_f32 v[132:133], v[132:133], s[68:69] op_sel_hi:[1,0]
	v_pk_mul_f32 v[134:135], v[134:135], s[68:69] op_sel_hi:[1,0]
	v_cvt_pk_bf16_f32 v128, v128, v129
	v_cvt_pk_bf16_f32 v129, v130, v131
	s_nop 0
	v_cvt_pk_bf16_f32 v130, v134, v135
	v_cvt_pk_bf16_f32 v131, v132, v133
	s_waitcnt vmcnt(0)
	v_pk_add_f32 v[220:221], v[224:225], v[220:221]
	v_pk_add_f32 v[218:219], v[222:223], v[218:219]
	v_pk_add_f32 v[222:223], v[228:229], v[232:233]
	v_pk_add_f32 v[224:225], v[226:227], v[230:231]
	v_pk_mul_f32 v[220:221], v[220:221], s[68:69] op_sel_hi:[1,0]
	v_pk_mul_f32 v[218:219], v[218:219], s[68:69] op_sel_hi:[1,0]
	v_pk_mul_f32 v[222:223], v[222:223], s[68:69] op_sel_hi:[1,0]
	v_pk_mul_f32 v[224:225], v[224:225], s[68:69] op_sel_hi:[1,0]
	v_cvt_pk_bf16_f32 v218, v218, v219
	v_cvt_pk_bf16_f32 v219, v220, v221
	s_nop 0
	v_cvt_pk_bf16_f32 v220, v224, v225
	v_cvt_pk_bf16_f32 v221, v222, v223
; #define MFMA32(a, b, c) __builtin_amdgcn_mfma_f32_32x32x16_bf16((a), (b), (c), 0, 0, 0)
; __device__ __forceinline__ void attn_phase(LAS unsigned char* lds, const bf16_t* Q, const bf16_t* Kb, const bf16_t* VT, const bf16_t* Z, const float* kpart, bf16_t* Y, int G, int bid) {
;     ...
;                     gacc = MFMA32(af, Qf[ks], gacc);
;                 }
;                 float gt[8];
; #pragma unroll
;                 for (int j = 0; j < 4; ++j) { const float mine = gacc[j], oth = __shfl_xor(mine, 32); gt[j] = hh == 0 ? mine : oth; gt[4 + j] = hh == 0 ? oth : mine; }
; #pragma unroll
;                 for (int j = 0; j < 8; ++j) if (j >= own) gt[j] = NEG;
;                 selmask = 0u;
; #pragma unroll
;                 for (int r = 0; r < 3; ++r) {
;                     float best = NEG; unsigned bi = 0u;
; #pragma unroll
;                     for (int j = 0; j < 8; ++j) { const bool take = !((selmask >> j) & 1u) && gt[j] > best; best = take ? gt[j] : best; bi = take ? (unsigned)j : bi; }
;                     selmask |= 1u << bi;
;                 }
.Lgate_skip:
	s_or_b64 exec, exec, s[0:1]
	s_waitcnt vmcnt(0)
	s_nop 1
	v_mfma_f32_32x32x16_bf16 v[0:15], v[0:3], v[96:99], 0
	v_mfma_f32_32x32x16_bf16 v[0:15], v[16:19], v[100:103], v[0:15]
	v_mfma_f32_32x32x16_bf16 v[0:15], v[32:35], v[104:107], v[0:15]
	v_mfma_f32_32x32x16_bf16 v[0:15], v[48:51], v[108:111], v[0:15]
	v_mfma_f32_32x32x16_bf16 v[0:15], v[64:67], v[112:115], v[0:15]
	v_mfma_f32_32x32x16_bf16 v[0:15], v[80:83], v[116:119], v[0:15]
	v_mfma_f32_32x32x16_bf16 v[0:15], v[128:131], v[120:123], v[0:15]
	v_mfma_f32_32x32x16_bf16 v[0:15], v[218:221], v[124:127], v[0:15]
	v_and_b32_e32 v21, 64, v175
	v_xor_b32_e32 v20, 32, v175
	v_add_u32_e32 v21, 64, v21
	v_cmp_lt_i32_e32 vcc, v20, v21
	s_cmp_lg_u32 s79, 4
	s_nop 0
	v_cndmask_b32_e32 v20, v175, v20, vcc
	s_nop 4
	v_lshlrev_b32_e32 v4, 2, v20
	ds_bpermute_b32 v5, v4, v0
	ds_bpermute_b32 v6, v4, v1
	ds_bpermute_b32 v7, v4, v2
	ds_bpermute_b32 v4, v4, v3
	s_cselect_b64 vcc, -1, 0
	s_waitcnt lgkmcnt(3)
	v_cndmask_b32_e64 v8, v5, v0, s[6:7]
	v_cndmask_b32_e64 v0, v0, v5, s[6:7]
	s_cmp_gt_u32 s79, 5
	s_waitcnt lgkmcnt(2)
	v_cndmask_b32_e64 v5, v6, v1, s[6:7]
	v_cndmask_b32_e64 v1, v1, v6, s[6:7]
	v_cndmask_b32_e32 v0, v177, v0, vcc
	s_cselect_b64 vcc, -1, 0
	s_cmp_eq_u32 s79, 7
	s_waitcnt lgkmcnt(1)
	v_cndmask_b32_e64 v6, v7, v2, s[6:7]
	v_cndmask_b32_e64 v2, v2, v7, s[6:7]
	v_cndmask_b32_e32 v1, v177, v1, vcc
	s_cselect_b64 vcc, -1, 0
	v_cndmask_b32_e32 v2, v177, v2, vcc
	v_cmp_lg_f32_e32 vcc, s72, v8
	s_waitcnt lgkmcnt(0)
	v_cndmask_b32_e64 v3, v4, v3, s[6:7]
	v_cmp_nlg_f32_e64 s[0:1], s72, v8
	v_cndmask_b32_e32 v4, v177, v8, vcc
	v_cmp_gt_f32_e32 vcc, v5, v4
	s_nop 1
	v_cndmask_b32_e32 v4, v4, v5, vcc
	v_cndmask_b32_e64 v7, 0, 1, vcc
	v_cmp_gt_f32_e32 vcc, v6, v4
	s_nop 1
	v_cndmask_b32_e32 v4, v4, v6, vcc
	v_cndmask_b32_e64 v7, v7, 2, vcc
	v_cmp_gt_f32_e32 vcc, v3, v4
	s_nop 1
	v_cndmask_b32_e32 v4, v4, v3, vcc
	v_cndmask_b32_e64 v7, v7, 3, vcc
	v_cmp_gt_f32_e32 vcc, v0, v4
	s_nop 1
	v_cndmask_b32_e32 v4, v4, v0, vcc
	v_cndmask_b32_e64 v7, v7, 4, vcc
	v_cmp_gt_f32_e32 vcc, v1, v4
	s_nop 1
	v_cndmask_b32_e32 v4, v4, v1, vcc
	v_cndmask_b32_e64 v7, v7, 5, vcc
	v_cmp_ngt_f32_e32 vcc, v2, v4
	s_nop 1
	v_cndmask_b32_e32 v4, 6, v7, vcc
	v_cmp_eq_u32_e32 vcc, 0, v4
	v_lshlrev_b32_e64 v7, v4, 1
	s_or_b64 vcc, s[0:1], vcc
	v_cndmask_b32_e32 v4, v8, v177, vcc
	v_and_b32_e32 v9, 2, v7
	v_cmp_eq_u32_e32 vcc, 0, v9
	v_cmp_gt_f32_e64 s[8:9], v5, v4
	s_and_b64 vcc, vcc, s[8:9]
	v_cndmask_b32_e32 v4, v4, v5, vcc
	v_and_b32_e32 v10, 4, v7
	v_cndmask_b32_e64 v9, 0, 1, vcc
	v_cmp_eq_u32_e32 vcc, 0, v10
	v_cmp_gt_f32_e64 s[8:9], v6, v4
	s_and_b64 vcc, vcc, s[8:9]
	v_cndmask_b32_e32 v4, v4, v6, vcc
	v_and_b32_e32 v10, 8, v7
	v_cmp_eq_u32_e64 s[8:9], 0, v10
	v_cmp_gt_f32_e64 s[10:11], v3, v4
	s_and_b64 s[8:9], s[8:9], s[10:11]
	v_cndmask_b32_e64 v4, v4, v3, s[8:9]
	v_and_b32_e32 v10, 16, v7
	v_cmp_eq_u32_e64 s[10:11], 0, v10
	v_cmp_gt_f32_e64 s[14:15], v0, v4
	s_and_b64 s[10:11], s[10:11], s[14:15]
	v_cndmask_b32_e64 v4, v4, v0, s[10:11]
	v_and_b32_e32 v10, 32, v7
	v_cmp_eq_u32_e64 s[14:15], 0, v10
	v_cmp_gt_f32_e64 s[16:17], v1, v4
	s_and_b64 s[14:15], s[14:15], s[16:17]
	v_cndmask_b32_e64 v4, v4, v1, s[14:15]
	v_cmp_gt_f32_e64 s[18:19], v2, v4
	v_lshlrev_b32_e64 v4, v9, 1
	v_cndmask_b32_e64 v4, v4, 4, vcc
	v_and_b32_e32 v10, 64, v7
	v_cndmask_b32_e64 v4, v4, 8, s[8:9]
	v_cmp_eq_u32_e64 s[16:17], 0, v10
	v_cndmask_b32_e64 v4, v4, 16, s[10:11]
	v_cndmask_b32_e64 v4, v4, 32, s[14:15]
	s_and_b64 s[8:9], s[16:17], s[18:19]
	v_cndmask_b32_e64 v4, v4, 64, s[8:9]
	v_or_b32_e32 v4, v4, v7
	v_and_b32_e32 v7, 1, v4
	v_cmp_eq_u32_e32 vcc, 1, v7
	s_or_b64 vcc, s[0:1], vcc
	s_nop 0
	v_cndmask_b32_e32 v7, v8, v177, vcc
	v_and_b32_e32 v8, 2, v4
	v_cmp_eq_u32_e32 vcc, 0, v8
	v_cmp_gt_f32_e64 s[0:1], v5, v7
	s_and_b64 vcc, vcc, s[0:1]
	v_cndmask_b32_e32 v5, v7, v5, vcc
	v_and_b32_e32 v7, 4, v4
	v_cndmask_b32_e64 v8, 0, 1, vcc
	v_cmp_eq_u32_e32 vcc, 0, v7
	v_cmp_gt_f32_e64 s[0:1], v6, v5
	s_and_b64 vcc, vcc, s[0:1]
	v_cndmask_b32_e32 v5, v5, v6, vcc
	v_and_b32_e32 v6, 8, v4
	v_cmp_eq_u32_e64 s[0:1], 0, v6
	v_cmp_gt_f32_e64 s[8:9], v3, v5
	s_and_b64 s[0:1], s[0:1], s[8:9]
	v_cndmask_b32_e64 v3, v5, v3, s[0:1]
	v_and_b32_e32 v5, 16, v4
	v_cmp_eq_u32_e64 s[8:9], 0, v5
	v_cmp_gt_f32_e64 s[10:11], v0, v3
	s_and_b64 s[8:9], s[8:9], s[10:11]
	v_cndmask_b32_e64 v0, v3, v0, s[8:9]
	v_and_b32_e32 v3, 32, v4
	v_cmp_eq_u32_e64 s[10:11], 0, v3
	v_cmp_gt_f32_e64 s[14:15], v1, v0
	s_and_b64 s[10:11], s[10:11], s[14:15]
	v_cndmask_b32_e64 v0, v0, v1, s[10:11]
	v_cmp_gt_f32_e64 s[16:17], v2, v0
	v_lshlrev_b32_e64 v0, v8, 1
	v_cndmask_b32_e64 v0, v0, 4, vcc
	v_and_b32_e32 v1, 64, v4
	v_cndmask_b32_e64 v0, v0, 8, s[0:1]
	v_cmp_eq_u32_e64 s[14:15], 0, v1
	v_cndmask_b32_e64 v0, v0, 16, s[8:9]
	v_cndmask_b32_e64 v0, v0, 32, s[10:11]
	s_and_b64 s[0:1], s[14:15], s[16:17]
	v_cndmask_b32_e64 v0, v0, 64, s[0:1]
	v_or_b32_e32 v181, v0, v4
